# r4a plus non-temporal (nt) cache hint on the read-once rownorm input-row loads in both rownorm loops
# speedup vs baseline: 1.0114x; 1.0086x over previous
; __device__ __forceinline__ void rownorm_phase(const XBuf xin, const float* mod_shift, const float* mod_scale, bf16_t* XN, int lane, int gw, int NGW) {
;     for (int row0 = gw * 2; row0 < T; row0 += NGW * 2) {
;         const int bi = batch_of(row0);
;         float v[2][4][8]; float ss0 = 0.f, ss1 = 0.f;
; #pragma unroll
;         for (int j = 0; j < 4; ++j) { xload8(xin, row0, 8 * lane + 512 * j, v[0][j]); xload8(xin, row0 + 1, 8 * lane + 512 * j, v[1][j]); }
; #pragma unroll
;         for (int j = 0; j < 4; ++j)
; #pragma unroll
;             for (int k = 0; k < 8; ++k) { ss0 += v[0][j][k] * v[0][j][k]; ss1 += v[1][j][k] * v[1][j][k]; }
;         const float rs0 = rsqrtf(wave_sum(ss0) * (1.0f / D) + EPS), rs1 = rsqrtf(wave_sum(ss1) * (1.0f / D) + EPS);
;         const float* sh = mod_shift + (size_t)bi * NMOD; const float* sc = mod_scale + (size_t)bi * NMOD;
; #pragma unroll
;         for (int j = 0; j < 4; ++j) { const int c = 8 * lane + 512 * j;
;             const f32x4 s0 = 1.0f + *(const f32x4*)(sc + c), s1 = 1.0f + *(const f32x4*)(sc + c + 4), h0 = *(const f32x4*)(sh + c), h1 = *(const f32x4*)(sh + c + 4);
.LBB0_514:
	s_add_i32 s0, s6, 0xffff8000
	s_lshr_b32 s0, s0, 6
	s_add_i32 s7, s0, 2
	s_cmp_lt_i32 s6, s28
	s_cselect_b32 s0, s30, s33
	s_cselect_b32 s1, s29, s31
	s_add_i32 s9, s6, 1
	s_cmp_lt_i32 s9, s28
	s_cselect_b32 s12, s30, s33
	s_cselect_b32 s13, s29, s31
	s_ashr_i32 s9, s6, 14
	s_cmp_lt_i32 s6, 0x8000
	v_lshl_add_u64 v[0:1], s[0:1], 0, v[34:35]
	s_cselect_b32 s0, s9, s7
	s_mul_hi_i32 s1, s0, 0xc000
	s_mul_i32 s0, s0, 0xc000
	v_lshl_add_u64 v[2:3], s[12:13], 0, v[34:35]
	s_add_u32 s12, s2, s0
	s_addc_u32 s13, s3, s1
	v_add_co_u32_e32 v2, vcc, s86, v2
	s_add_u32 s14, s16, s0
	s_nop 0
	v_addc_co_u32_e32 v3, vcc, 0, v3, vcc
	s_addc_u32 s15, s17, s1
	global_load_dwordx4 v[36:39], v[0:1], off nt
	global_load_dwordx4 v[40:43], v[2:3], off nt
	global_load_dwordx4 v[26:29], v[0:1], off offset:1024 nt
	global_load_dwordx4 v[30:33], v[2:3], off offset:1024 nt
	global_load_dwordx4 v[18:21], v[0:1], off offset:2048 nt
	global_load_dwordx4 v[22:25], v[2:3], off offset:2048 nt
	global_load_dwordx4 v[10:13], v[0:1], off offset:3072 nt
	global_load_dwordx4 v[14:17], v[2:3], off offset:3072 nt
	s_nop 0
	global_load_dwordx4 v[2:5], v98, s[14:15] offset:16
	global_load_dwordx4 v[6:9], v98, s[14:15]
	global_load_dwordx4 v[116:119], v98, s[12:13] offset:16
	global_load_dwordx4 v[120:123], v98, s[12:13]
	global_load_dwordx4 v[124:127], v98, s[14:15] offset:2064
	global_load_dwordx4 v[128:131], v98, s[14:15] offset:2048
	global_load_dwordx4 v[132:135], v98, s[12:13] offset:2064
	global_load_dwordx4 v[136:139], v98, s[12:13] offset:2048
	global_load_dwordx4 v[140:143], v99, s[14:15] offset:16
	global_load_dwordx4 v[144:147], v99, s[14:15]
	global_load_dwordx4 v[148:151], v99, s[12:13] offset:16
	global_load_dwordx4 v[152:155], v99, s[12:13]
	global_load_dwordx4 v[156:159], v100, s[14:15] offset:16
	global_load_dwordx4 v[168:171], v100, s[14:15]
	global_load_dwordx4 v[172:175], v100, s[12:13] offset:16
	global_load_dwordx4 v[176:179], v100, s[12:13]
	v_lshl_add_u64 v[66:67], s[20:21], 0, v[34:35]
	s_add_i32 s6, s6, s8
	v_lshl_add_u64 v[34:35], v[34:35], 0, s[10:11]
	s_cmp_gt_i32 s6, 0x87ff
	s_waitcnt vmcnt(0)
	v_and_b32_e32 v63, 0xffff0000, v40
	v_lshlrev_b32_e32 v62, 16, v40
	v_mov_b32_e32 v50, v63
	v_lshlrev_b32_e32 v60, 16, v41
	v_mov_b32_e32 v46, v62
	v_and_b32_e32 v81, 0xffff0000, v36
	v_pk_add_f32 v[68:69], v[4:5], 1.0 op_sel_hi:[1,0]
	v_pk_add_f32 v[70:71], v[8:9], 1.0 op_sel_hi:[1,0]
	v_pk_add_f32 v[0:1], v[6:7], 1.0 op_sel_hi:[1,0]
	v_pk_add_f32 v[72:73], v[2:3], 1.0 op_sel_hi:[1,0]
	v_mov_b32_e32 v2, v116
	v_mov_b32_e32 v3, v117
	v_mov_b32_e32 v4, v118
	v_mov_b32_e32 v5, v119
	v_mov_b32_e32 v6, v120
	v_mov_b32_e32 v7, v121
	v_mov_b32_e32 v8, v122
	v_mov_b32_e32 v9, v123
	v_lshlrev_b32_e32 v80, 16, v36
	v_mov_b32_e32 v51, v81
	v_lshlrev_b32_e32 v78, 16, v37
	v_mov_b32_e32 v47, v80
	v_pk_mul_f32 v[50:51], v[50:51], v[50:51]
	v_and_b32_e32 v79, 0xffff0000, v37
	v_lshlrev_b32_e32 v56, 16, v43
	v_and_b32_e32 v57, 0xffff0000, v43
	v_lshlrev_b32_e32 v58, 16, v42
	v_and_b32_e32 v59, 0xffff0000, v42
	v_and_b32_e32 v61, 0xffff0000, v41
	v_mov_b32_e32 v42, v60
	v_mov_b32_e32 v43, v78
	v_pk_fma_f32 v[46:47], v[46:47], v[46:47], v[50:51]
	v_lshlrev_b32_e32 v76, 16, v38
	v_mov_b32_e32 v44, v61
	v_mov_b32_e32 v45, v79
	v_pk_fma_f32 v[42:43], v[42:43], v[42:43], v[46:47]
	v_lshlrev_b32_e32 v74, 16, v39
	v_and_b32_e32 v75, 0xffff0000, v39
	v_and_b32_e32 v77, 0xffff0000, v38
	v_mov_b32_e32 v38, v58
	v_mov_b32_e32 v39, v76
	v_pk_fma_f32 v[42:43], v[44:45], v[44:45], v[42:43]
	v_mov_b32_e32 v40, v59
	v_mov_b32_e32 v41, v77
	v_pk_fma_f32 v[38:39], v[38:39], v[38:39], v[42:43]
	v_mov_b32_e32 v36, v56
	v_mov_b32_e32 v37, v74
	v_pk_fma_f32 v[38:39], v[40:41], v[40:41], v[38:39]
	v_mov_b32_e32 v48, v57
	v_mov_b32_e32 v49, v75
	v_pk_fma_f32 v[50:51], v[36:37], v[36:37], v[38:39]
	v_lshlrev_b32_e32 v86, 16, v30
	v_lshlrev_b32_e32 v38, 16, v26
	v_and_b32_e32 v87, 0xffff0000, v30
	v_and_b32_e32 v39, 0xffff0000, v26
	v_lshlrev_b32_e32 v44, 16, v19
	v_and_b32_e32 v45, 0xffff0000, v19
	v_lshlrev_b32_e32 v46, 16, v18
	v_and_b32_e32 v47, 0xffff0000, v18
	v_pk_fma_f32 v[18:19], v[48:49], v[48:49], v[50:51]
	v_mov_b32_e32 v102, v86
	v_mov_b32_e32 v103, v38
	v_lshlrev_b32_e32 v84, 16, v31
	v_lshlrev_b32_e32 v36, 16, v27
	v_mov_b32_e32 v104, v87
	v_mov_b32_e32 v105, v39
	v_pk_fma_f32 v[18:19], v[102:103], v[102:103], v[18:19]
	v_and_b32_e32 v85, 0xffff0000, v31
	v_and_b32_e32 v37, 0xffff0000, v27
	v_mov_b32_e32 v52, v84
	v_mov_b32_e32 v53, v36
	v_pk_fma_f32 v[18:19], v[104:105], v[104:105], v[18:19]
	v_lshlrev_b32_e32 v82, 16, v32
	v_and_b32_e32 v83, 0xffff0000, v32
	v_lshlrev_b32_e32 v32, 16, v28
	v_mov_b32_e32 v54, v85
	v_mov_b32_e32 v55, v37
	v_pk_fma_f32 v[18:19], v[52:53], v[52:53], v[18:19]
	v_lshlrev_b32_e32 v64, 16, v33
	v_and_b32_e32 v65, 0xffff0000, v33
	v_and_b32_e32 v33, 0xffff0000, v28
	v_mov_b32_e32 v48, v82
	v_mov_b32_e32 v49, v32
	v_pk_fma_f32 v[18:19], v[54:55], v[54:55], v[18:19]
	v_lshlrev_b32_e32 v30, 16, v29
	v_mov_b32_e32 v50, v83
	v_mov_b32_e32 v51, v33
	v_pk_fma_f32 v[18:19], v[48:49], v[48:49], v[18:19]
	v_and_b32_e32 v31, 0xffff0000, v29
	v_lshlrev_b32_e32 v40, 16, v21
	v_and_b32_e32 v41, 0xffff0000, v21
	v_lshlrev_b32_e32 v42, 16, v20
	v_and_b32_e32 v43, 0xffff0000, v20
	v_mov_b32_e32 v20, v64
	v_mov_b32_e32 v21, v30
	v_pk_fma_f32 v[18:19], v[50:51], v[50:51], v[18:19]
	v_lshlrev_b32_e32 v88, 16, v25
	v_and_b32_e32 v89, 0xffff0000, v25
	v_lshlrev_b32_e32 v90, 16, v24
	v_and_b32_e32 v91, 0xffff0000, v24
	v_lshlrev_b32_e32 v24, 16, v23
	v_and_b32_e32 v25, 0xffff0000, v23
	v_lshlrev_b32_e32 v26, 16, v22
	v_and_b32_e32 v27, 0xffff0000, v22
	v_mov_b32_e32 v22, v65
; __device__ __forceinline__ unsigned pk2(float lo, float hi) { const f32x2 v = {lo, hi}; return __builtin_bit_cast(unsigned, __builtin_convertvector(v, bf16x2_t)); }
; __device__ __forceinline__ void rownorm_phase(const XBuf xin, const float* mod_shift, const float* mod_scale, bf16_t* XN, int lane, int gw, int NGW) {
;     ...
;             for (int k = 0; k < 8; ++k) { ss0 += v[0][j][k] * v[0][j][k]; ss1 += v[1][j][k] * v[1][j][k]; }
;         const float rs0 = rsqrtf(wave_sum(ss0) * (1.0f / D) + EPS), rs1 = rsqrtf(wave_sum(ss1) * (1.0f / D) + EPS);
;         const float* sh = mod_shift + (size_t)bi * NMOD; const float* sc = mod_scale + (size_t)bi * NMOD;
; #pragma unroll
;         for (int j = 0; j < 4; ++j) { const int c = 8 * lane + 512 * j;
;             const f32x4 s0 = 1.0f + *(const f32x4*)(sc + c), s1 = 1.0f + *(const f32x4*)(sc + c + 4), h0 = *(const f32x4*)(sh + c), h1 = *(const f32x4*)(sh + c + 4);
;             u32x4 w0, w1;
;             w0.x = pk2(v[0][j][0] * rs0 * s0[0] + h0[0], v[0][j][1] * rs0 * s0[1] + h0[1]); w0.y = pk2(v[0][j][2] * rs0 * s0[2] + h0[2], v[0][j][3] * rs0 * s0[3] + h0[3]);
;             w0.z = pk2(v[0][j][4] * rs0 * s1[0] + h1[0], v[0][j][5] * rs0 * s1[1] + h1[1]); w0.w = pk2(v[0][j][6] * rs0 * s1[2] + h1[2], v[0][j][7] * rs0 * s1[3] + h1[3]);
;             w1.x = pk2(v[1][j][0] * rs1 * s0[0] + h0[0], v[1][j][1] * rs1 * s0[1] + h0[1]); w1.y = pk2(v[1][j][2] * rs1 * s0[2] + h0[2], v[1][j][3] * rs1 * s0[3] + h0[3]);
;             w1.z = pk2(v[1][j][4] * rs1 * s1[0] + h1[0], v[1][j][5] * rs1 * s1[1] + h1[1]); w1.w = pk2(v[1][j][6] * rs1 * s1[2] + h1[2], v[1][j][7] * rs1 * s1[3] + h1[3]);
	v_mov_b32_e32 v23, v31
	v_pk_fma_f32 v[18:19], v[20:21], v[20:21], v[18:19]
	v_mov_b32_e32 v20, v26
	v_pk_fma_f32 v[18:19], v[22:23], v[22:23], v[18:19]
	v_mov_b32_e32 v21, v46
	v_mov_b32_e32 v22, v27
	v_mov_b32_e32 v23, v47
	v_pk_fma_f32 v[18:19], v[20:21], v[20:21], v[18:19]
	v_mov_b32_e32 v28, v24
	v_mov_b32_e32 v29, v44
	v_pk_fma_f32 v[102:103], v[22:23], v[22:23], v[18:19]
	v_mov_b32_e32 v114, v25
	v_mov_b32_e32 v115, v45
	v_pk_fma_f32 v[28:29], v[28:29], v[28:29], v[102:103]
	v_mov_b32_e32 v110, v90
	v_mov_b32_e32 v111, v42
	v_pk_fma_f32 v[28:29], v[114:115], v[114:115], v[28:29]
	v_mov_b32_e32 v112, v91
	v_mov_b32_e32 v113, v43
	v_pk_fma_f32 v[28:29], v[110:111], v[110:111], v[28:29]
	v_lshlrev_b32_e32 v52, 16, v11
	v_and_b32_e32 v53, 0xffff0000, v11
	v_lshlrev_b32_e32 v54, 16, v10
	v_and_b32_e32 v55, 0xffff0000, v10
	v_mov_b32_e32 v10, v88
	v_mov_b32_e32 v11, v40
	v_pk_fma_f32 v[28:29], v[112:113], v[112:113], v[28:29]
	v_lshlrev_b32_e32 v22, 16, v14
	v_mov_b32_e32 v108, v89
	v_mov_b32_e32 v109, v41
	v_pk_fma_f32 v[10:11], v[10:11], v[10:11], v[28:29]
	v_and_b32_e32 v23, 0xffff0000, v14
	v_pk_fma_f32 v[10:11], v[108:109], v[108:109], v[10:11]
	v_mov_b32_e32 v108, v22
	v_mov_b32_e32 v109, v54
	v_lshlrev_b32_e32 v20, 16, v16
	v_and_b32_e32 v21, 0xffff0000, v16
	v_lshlrev_b32_e32 v16, 16, v15
	v_mov_b32_e32 v110, v23
	v_mov_b32_e32 v111, v55
	v_pk_fma_f32 v[10:11], v[108:109], v[108:109], v[10:11]
	v_lshlrev_b32_e32 v18, 16, v17
	v_and_b32_e32 v19, 0xffff0000, v17
	v_and_b32_e32 v17, 0xffff0000, v15
	v_lshlrev_b32_e32 v50, 16, v12
	v_and_b32_e32 v51, 0xffff0000, v12
	v_mov_b32_e32 v28, v16
	v_mov_b32_e32 v29, v52
	v_pk_fma_f32 v[10:11], v[110:111], v[110:111], v[10:11]
	v_pk_mul_f32 v[106:107], v[20:21], v[20:21]
	v_lshlrev_b32_e32 v48, 16, v13
	v_and_b32_e32 v49, 0xffff0000, v13
	v_pk_mul_f32 v[12:13], v[50:51], v[50:51]
	v_mov_b32_e32 v102, v17
	v_mov_b32_e32 v103, v53
	v_pk_fma_f32 v[10:11], v[28:29], v[28:29], v[10:11]
	v_mov_b32_e32 v28, v106
	v_pk_fma_f32 v[10:11], v[102:103], v[102:103], v[10:11]
	v_mov_b32_e32 v29, v12
	v_pk_mul_f32 v[104:105], v[18:19], v[18:19]
	v_pk_mul_f32 v[14:15], v[48:49], v[48:49]
	v_pk_add_f32 v[10:11], v[28:29], v[10:11]
	v_mov_b32_e32 v12, v107
	v_pk_add_f32 v[10:11], v[12:13], v[10:11]
	v_mov_b32_e32 v12, v104
	v_mov_b32_e32 v13, v14
	v_pk_add_f32 v[10:11], v[12:13], v[10:11]
	v_mov_b32_e32 v14, v105
	v_pk_add_f32 v[10:11], v[14:15], v[10:11]
	ds_bpermute_b32 v12, v92, v10
	ds_bpermute_b32 v13, v92, v11
	s_waitcnt lgkmcnt(0)
	v_pk_add_f32 v[10:11], v[10:11], v[12:13]
	ds_bpermute_b32 v12, v93, v10
	ds_bpermute_b32 v13, v93, v11
	s_waitcnt lgkmcnt(0)
	v_pk_add_f32 v[10:11], v[10:11], v[12:13]
	ds_bpermute_b32 v12, v94, v10
	ds_bpermute_b32 v13, v94, v11
	s_waitcnt lgkmcnt(0)
	v_pk_add_f32 v[10:11], v[10:11], v[12:13]
	ds_bpermute_b32 v12, v95, v10
	ds_bpermute_b32 v13, v95, v11
	s_waitcnt lgkmcnt(0)
	v_pk_add_f32 v[10:11], v[10:11], v[12:13]
	ds_bpermute_b32 v12, v96, v10
	ds_bpermute_b32 v13, v96, v11
	s_waitcnt lgkmcnt(0)
	v_pk_add_f32 v[10:11], v[10:11], v[12:13]
	ds_bpermute_b32 v12, v97, v10
	ds_bpermute_b32 v13, v97, v11
	s_waitcnt lgkmcnt(0)
	v_pk_add_f32 v[10:11], v[10:11], v[12:13]
	s_nop 0
	v_pk_fma_f32 v[10:11], v[10:11], s[18:19], v[162:163] op_sel_hi:[1,0,0]
	s_nop 0
	v_mul_f32_e32 v12, 0x4b800000, v10
	v_cmp_gt_f32_e64 s[0:1], s91, v10
	v_cmp_gt_f32_e32 vcc, s91, v11
	s_nop 0
	v_cndmask_b32_e64 v10, v10, v12, s[0:1]
	v_rsq_f32_e32 v10, v10
	s_nop 0
	v_mul_f32_e32 v12, 0x45800000, v10
	v_cndmask_b32_e64 v10, v10, v12, s[0:1]
	v_pk_mul_f32 v[12:13], v[10:11], v[62:63] op_sel_hi:[0,1]
	v_pk_fma_f32 v[12:13], v[0:1], v[12:13], v[6:7]
	v_pk_mul_f32 v[62:63], v[10:11], v[86:87] op_sel_hi:[0,1]
	v_cvt_pk_bf16_f32 v102, v12, v13
	v_pk_mul_f32 v[12:13], v[10:11], v[60:61] op_sel_hi:[0,1]
	v_pk_fma_f32 v[12:13], v[70:71], v[12:13], v[8:9]
	v_pk_mul_f32 v[60:61], v[10:11], v[84:85] op_sel_hi:[0,1]
	v_cvt_pk_bf16_f32 v103, v12, v13
	v_pk_mul_f32 v[12:13], v[10:11], v[58:59] op_sel_hi:[0,1]
	v_pk_fma_f32 v[12:13], v[72:73], v[12:13], v[2:3]
	v_pk_mul_f32 v[58:59], v[10:11], v[82:83] op_sel_hi:[0,1]
	v_cvt_pk_bf16_f32 v104, v12, v13
	v_pk_mul_f32 v[12:13], v[10:11], v[56:57] op_sel_hi:[0,1]
	v_pk_mul_f32 v[56:57], v[10:11], v[64:65] op_sel_hi:[0,1]
	v_mul_f32_e32 v64, 0x4b800000, v11
	v_pk_mul_f32 v[28:29], v[10:11], v[26:27] op_sel_hi:[0,1]
	v_pk_mul_f32 v[26:27], v[10:11], v[24:25] op_sel_hi:[0,1]
	v_pk_mul_f32 v[24:25], v[10:11], v[90:91] op_sel_hi:[0,1]
	v_pk_mul_f32 v[14:15], v[10:11], v[88:89] op_sel_hi:[0,1]
	v_cndmask_b32_e32 v11, v11, v64, vcc
	v_rsq_f32_e32 v11, v11
	v_pk_fma_f32 v[12:13], v[68:69], v[12:13], v[4:5]
	s_mov_b32 s0, 0x11401000
	v_cvt_pk_bf16_f32 v105, v12, v13
	v_mul_f32_e32 v64, 0x45800000, v11
	v_cndmask_b32_e32 v64, v11, v64, vcc
	v_pk_mul_f32 v[80:81], v[64:65], v[80:81] op_sel_hi:[0,1]
	v_pk_fma_f32 v[0:1], v[0:1], v[80:81], v[6:7]
	v_pk_mul_f32 v[6:7], v[64:65], v[78:79] op_sel_hi:[0,1]
	v_pk_fma_f32 v[6:7], v[70:71], v[6:7], v[8:9]
	v_add_co_u32_e64 v12, s[0:1], s0, v66
	v_cvt_pk_bf16_f32 v0, v0, v1
	v_cvt_pk_bf16_f32 v1, v6, v7
	v_pk_mul_f32 v[6:7], v[64:65], v[76:77] op_sel_hi:[0,1]
	v_addc_co_u32_e64 v13, s[0:1], 0, v67, s[0:1]
	v_pk_fma_f32 v[2:3], v[72:73], v[6:7], v[2:3]
	v_pk_mul_f32 v[6:7], v[64:65], v[74:75] op_sel_hi:[0,1]
	v_pk_fma_f32 v[4:5], v[68:69], v[6:7], v[4:5]
	s_mov_b32 s0, 0x11400000
	v_cvt_pk_bf16_f32 v2, v2, v3
; __device__ __forceinline__ unsigned pk2(float lo, float hi) { const f32x2 v = {lo, hi}; return __builtin_bit_cast(unsigned, __builtin_convertvector(v, bf16x2_t)); }
; __device__ __forceinline__ void rownorm_phase(const XBuf xin, const float* mod_shift, const float* mod_scale, bf16_t* XN, int lane, int gw, int NGW) {
;     ...
;         for (int j = 0; j < 4; ++j) { const int c = 8 * lane + 512 * j;
;             const f32x4 s0 = 1.0f + *(const f32x4*)(sc + c), s1 = 1.0f + *(const f32x4*)(sc + c + 4), h0 = *(const f32x4*)(sh + c), h1 = *(const f32x4*)(sh + c + 4);
;             u32x4 w0, w1;
;             w0.x = pk2(v[0][j][0] * rs0 * s0[0] + h0[0], v[0][j][1] * rs0 * s0[1] + h0[1]); w0.y = pk2(v[0][j][2] * rs0 * s0[2] + h0[2], v[0][j][3] * rs0 * s0[3] + h0[3]);
;             w0.z = pk2(v[0][j][4] * rs0 * s1[0] + h1[0], v[0][j][5] * rs0 * s1[1] + h1[1]); w0.w = pk2(v[0][j][6] * rs0 * s1[2] + h1[2], v[0][j][7] * rs0 * s1[3] + h1[3]);
;             w1.x = pk2(v[1][j][0] * rs1 * s0[0] + h0[0], v[1][j][1] * rs1 * s0[1] + h0[1]); w1.y = pk2(v[1][j][2] * rs1 * s0[2] + h0[2], v[1][j][3] * rs1 * s0[3] + h0[3]);
;             w1.z = pk2(v[1][j][4] * rs1 * s1[0] + h1[0], v[1][j][5] * rs1 * s1[1] + h1[1]); w1.w = pk2(v[1][j][6] * rs1 * s1[2] + h1[2], v[1][j][7] * rs1 * s1[3] + h1[3]);
;             *(u32x4*)(XN + (size_t)row0 * D + c) = w0; *(u32x4*)(XN + (size_t)(row0 + 1) * D + c) = w1; }
	v_cvt_pk_bf16_f32 v3, v4, v5
	v_add_co_u32_e32 v4, vcc, s0, v66
	global_store_dwordx4 v[12:13], v[102:105], off
	s_nop 0
	v_addc_co_u32_e32 v5, vcc, 0, v67, vcc
	global_store_dwordx4 v[4:5], v[0:3], off
	v_pk_mul_f32 v[66:67], v[64:65], v[38:39] op_sel_hi:[0,1]
	v_pk_mul_f32 v[68:69], v[64:65], v[36:37] op_sel_hi:[0,1]
	v_pk_mul_f32 v[70:71], v[64:65], v[32:33] op_sel_hi:[0,1]
	v_pk_mul_f32 v[72:73], v[64:65], v[30:31] op_sel_hi:[0,1]
	v_pk_mul_f32 v[38:39], v[64:65], v[46:47] op_sel_hi:[0,1]
	v_pk_mul_f32 v[36:37], v[64:65], v[44:45] op_sel_hi:[0,1]
	v_pk_mul_f32 v[32:33], v[64:65], v[42:43] op_sel_hi:[0,1]
	v_pk_mul_f32 v[30:31], v[64:65], v[40:41] op_sel_hi:[0,1]
	v_mov_b32_e32 v40, v124
	v_mov_b32_e32 v41, v125
	v_mov_b32_e32 v42, v126
	v_mov_b32_e32 v43, v127
	v_mov_b32_e32 v44, v128
	v_mov_b32_e32 v45, v129
	v_mov_b32_e32 v46, v130
	v_mov_b32_e32 v47, v131
	v_pk_mul_f32 v[8:9], v[64:65], v[54:55] op_sel_hi:[0,1]
	v_pk_mul_f32 v[6:7], v[64:65], v[52:53] op_sel_hi:[0,1]
	v_pk_mul_f32 v[2:3], v[64:65], v[50:51] op_sel_hi:[0,1]
	v_pk_mul_f32 v[0:1], v[64:65], v[48:49] op_sel_hi:[0,1]
	v_pk_add_f32 v[64:65], v[42:43], 1.0 op_sel_hi:[1,0]
	v_pk_add_f32 v[52:53], v[46:47], 1.0 op_sel_hi:[1,0]
	v_pk_add_f32 v[54:55], v[44:45], 1.0 op_sel_hi:[1,0]
	v_pk_add_f32 v[74:75], v[40:41], 1.0 op_sel_hi:[1,0]
	v_mov_b32_e32 v40, v132
	v_mov_b32_e32 v41, v133
	v_mov_b32_e32 v42, v134
	v_mov_b32_e32 v43, v135
	v_mov_b32_e32 v44, v136
	v_mov_b32_e32 v45, v137
	v_mov_b32_e32 v46, v138
	v_mov_b32_e32 v47, v139
	v_pk_fma_f32 v[48:49], v[54:55], v[66:67], v[44:45]
	v_pk_fma_f32 v[50:51], v[52:53], v[68:69], v[46:47]
	v_cvt_pk_bf16_f32 v48, v48, v49
	v_cvt_pk_bf16_f32 v49, v50, v51
	v_pk_fma_f32 v[50:51], v[74:75], v[70:71], v[40:41]
	v_pk_fma_f32 v[66:67], v[64:65], v[72:73], v[42:43]
	v_pk_fma_f32 v[44:45], v[54:55], v[62:63], v[44:45]
	v_pk_fma_f32 v[46:47], v[52:53], v[60:61], v[46:47]
	v_pk_fma_f32 v[40:41], v[74:75], v[58:59], v[40:41]
	v_cvt_pk_bf16_f32 v50, v50, v51
	v_cvt_pk_bf16_f32 v51, v66, v67
	v_cvt_pk_bf16_f32 v44, v44, v45
	v_cvt_pk_bf16_f32 v45, v46, v47
	v_cvt_pk_bf16_f32 v46, v40, v41
	v_pk_fma_f32 v[40:41], v[64:65], v[56:57], v[42:43]
	s_nop 0
	v_cvt_pk_bf16_f32 v47, v40, v41
	global_store_dwordx4 v[4:5], v[48:51], off offset:1024
	global_store_dwordx4 v[12:13], v[44:47], off offset:1024
	s_nop 1
	v_mov_b32_e32 v40, v140
	v_mov_b32_e32 v41, v141
	v_mov_b32_e32 v42, v142
	v_mov_b32_e32 v43, v143
	s_nop 0
	s_nop 1
	v_mov_b32_e32 v44, v144
	v_mov_b32_e32 v45, v145
	v_mov_b32_e32 v46, v146
	v_mov_b32_e32 v47, v147
	v_pk_add_f32 v[56:57], v[42:43], 1.0 op_sel_hi:[1,0]
	v_pk_add_f32 v[52:53], v[46:47], 1.0 op_sel_hi:[1,0]
	v_pk_add_f32 v[54:55], v[44:45], 1.0 op_sel_hi:[1,0]
	v_pk_add_f32 v[58:59], v[40:41], 1.0 op_sel_hi:[1,0]
	v_mov_b32_e32 v40, v148
	v_mov_b32_e32 v41, v149
	v_mov_b32_e32 v42, v150
	v_mov_b32_e32 v43, v151
	v_mov_b32_e32 v44, v152
	v_mov_b32_e32 v45, v153
	v_mov_b32_e32 v46, v154
	v_mov_b32_e32 v47, v155
	v_pk_fma_f32 v[32:33], v[58:59], v[32:33], v[40:41]
	v_pk_fma_f32 v[38:39], v[54:55], v[38:39], v[44:45]
	v_pk_fma_f32 v[36:37], v[52:53], v[36:37], v[46:47]
	v_pk_fma_f32 v[30:31], v[56:57], v[30:31], v[42:43]
	v_cvt_pk_bf16_f32 v48, v38, v39
	v_cvt_pk_bf16_f32 v49, v36, v37
	v_cvt_pk_bf16_f32 v50, v32, v33
	v_cvt_pk_bf16_f32 v51, v30, v31
	v_pk_fma_f32 v[28:29], v[54:55], v[28:29], v[44:45]
	v_pk_fma_f32 v[26:27], v[52:53], v[26:27], v[46:47]
	v_pk_fma_f32 v[24:25], v[58:59], v[24:25], v[40:41]
	v_pk_fma_f32 v[14:15], v[56:57], v[14:15], v[42:43]
	v_cvt_pk_bf16_f32 v28, v28, v29
	v_cvt_pk_bf16_f32 v29, v26, v27
	v_cvt_pk_bf16_f32 v30, v24, v25
	v_cvt_pk_bf16_f32 v31, v14, v15
	global_store_dwordx4 v[4:5], v[48:51], off offset:2048
	global_store_dwordx4 v[12:13], v[28:31], off offset:2048
	s_nop 1
	v_mov_b32_e32 v24, v156
	v_mov_b32_e32 v25, v157
	v_mov_b32_e32 v26, v158
	v_mov_b32_e32 v27, v159
	s_nop 0
	s_nop 1
	v_mov_b32_e32 v28, v168
	v_mov_b32_e32 v29, v169
	v_mov_b32_e32 v30, v170
	v_mov_b32_e32 v31, v171
	v_pk_add_f32 v[40:41], v[26:27], 1.0 op_sel_hi:[1,0]
	v_pk_add_f32 v[14:15], v[30:31], 1.0 op_sel_hi:[1,0]
	v_pk_add_f32 v[32:33], v[28:29], 1.0 op_sel_hi:[1,0]
	v_pk_add_f32 v[42:43], v[24:25], 1.0 op_sel_hi:[1,0]
	v_mov_b32_e32 v24, v172
	v_mov_b32_e32 v25, v173
	v_mov_b32_e32 v26, v174
	v_mov_b32_e32 v27, v175
	v_mov_b32_e32 v28, v176
	v_mov_b32_e32 v29, v177
	v_mov_b32_e32 v30, v178
	v_mov_b32_e32 v31, v179
	v_pk_fma_f32 v[2:3], v[42:43], v[2:3], v[24:25]
	v_pk_fma_f32 v[0:1], v[40:41], v[0:1], v[26:27]
	v_cvt_pk_bf16_f32 v38, v2, v3
	v_cvt_pk_bf16_f32 v39, v0, v1
	v_pk_mul_f32 v[0:1], v[10:11], v[22:23] op_sel_hi:[0,1]
	v_pk_mul_f32 v[2:3], v[10:11], v[16:17] op_sel_hi:[0,1]
	v_pk_fma_f32 v[6:7], v[14:15], v[6:7], v[30:31]
	v_pk_fma_f32 v[0:1], v[32:33], v[0:1], v[28:29]
	v_pk_fma_f32 v[2:3], v[14:15], v[2:3], v[30:31]
	v_pk_fma_f32 v[8:9], v[32:33], v[8:9], v[28:29]
	v_cvt_pk_bf16_f32 v37, v6, v7
	v_cvt_pk_bf16_f32 v0, v0, v1
	v_cvt_pk_bf16_f32 v1, v2, v3
	v_pk_mul_f32 v[2:3], v[10:11], v[20:21] op_sel_hi:[0,1]
	v_pk_mul_f32 v[6:7], v[10:11], v[18:19] op_sel_hi:[0,1]
	v_cvt_pk_bf16_f32 v36, v8, v9
	v_pk_fma_f32 v[2:3], v[42:43], v[2:3], v[24:25]
	v_pk_fma_f32 v[6:7], v[40:41], v[6:7], v[26:27]
	v_cvt_pk_bf16_f32 v2, v2, v3
	v_cvt_pk_bf16_f32 v3, v6, v7
	global_store_dwordx4 v[4:5], v[36:39], off offset:3072
	global_store_dwordx4 v[12:13], v[0:3], off offset:3072
	s_cbranch_scc0 .LBB0_514

; __device__ __forceinline__ void unpack8(u32x4 w, float* f) { f[0] = bflo(w.x); f[1] = bfhi(w.x); f[2] = bflo(w.y); f[3] = bfhi(w.y); f[4] = bflo(w.z); f[5] = bfhi(w.z); f[6] = bflo(w.w); f[7] = bfhi(w.w); }
; __device__ __forceinline__ const unsigned char* xrow(const XBuf& b, int row) { return (row < b.split ? b.p0 : b.p1) + (size_t)row * (b.f32 ? 8192 : 4096); }
; __device__ __forceinline__ void xload8(const XBuf& b, int row, int col, float* v) {
;     const unsigned char* r = xrow(b, row);
;     if (b.f32) { const f32x4 a0 = *(const f32x4*)(r + (size_t)col * 4), a1 = *(const f32x4*)(r + (size_t)col * 4 + 16);
; #pragma unroll
;         for (int j = 0; j < 4; ++j) { v[j] = a0[j]; v[4 + j] = a1[j]; } }
;     else unpack8(*(const u32x4*)(r + (size_t)col * 2), v);
; __device__ __forceinline__ void rownorm_phase(const XBuf xin, const float* mod_shift, const float* mod_scale, bf16_t* XN, int lane, int gw, int NGW) {
;     ...
;         for (int j = 0; j < 4; ++j) { xload8(xin, row0, 8 * lane + 512 * j, v[0][j]); xload8(xin, row0 + 1, 8 * lane + 512 * j, v[1][j]); }
.LBB0_797:
	v_readlane_b32 s0, v254, 41
	s_cmp_lt_i32 s4, s0
	v_readlane_b32 s0, v254, 38
	s_cselect_b32 s2, s77, s0
	v_readlane_b32 s0, v254, 36
	v_readlane_b32 s1, v254, 40
	s_cselect_b32 s3, s0, s1
	s_add_u32 s0, s10, -1
	s_addc_u32 s1, s11, -1
	s_lshl_b64 s[0:1], s[0:1], s18
	v_readlane_b32 s12, v254, 31
	s_add_u32 s0, s3, s0
	v_readlane_b32 s13, v254, 32
	s_addc_u32 s1, s2, s1
	s_mov_b64 s[2:3], -1
	s_and_b64 vcc, exec, s[12:13]
	s_cbranch_vccz .LBB0_799
	v_lshl_add_u64 v[0:1], s[0:1], 0, v[64:65]
	global_load_dwordx4 v[0:3], v[0:1], off nt
	s_mov_b64 s[2:3], 0
.LBB0_799:
	s_andn2_b64 vcc, exec, s[2:3]
	s_cbranch_vccnz .LBB0_801
	v_lshl_add_u64 v[4:5], s[0:1], 0, v[160:161]
	global_load_dwordx4 v[0:3], v[4:5], off offset:16 nt
	s_nop 0
	global_load_dwordx4 v[4:7], v[4:5], off nt
.LBB0_801:
	v_readlane_b32 s2, v254, 41
	s_cmp_lt_i32 s10, s2
	v_readlane_b32 s2, v254, 38
	s_cselect_b32 s5, s77, s2
	v_readlane_b32 s2, v254, 36
	v_readlane_b32 s3, v254, 40
	s_cselect_b32 s12, s2, s3
	s_lshl_b64 s[2:3], s[10:11], s18
	v_readlane_b32 s14, v254, 31
	s_add_u32 s12, s12, s2
	v_readlane_b32 s15, v254, 32
	s_addc_u32 s13, s5, s3
	s_mov_b64 s[2:3], -1
	s_and_b64 vcc, exec, s[14:15]
	s_cbranch_vccz .LBB0_803
	v_lshl_add_u64 v[8:9], s[12:13], 0, v[64:65]
	global_load_dwordx4 v[8:11], v[8:9], off nt
	s_mov_b64 s[2:3], 0
.LBB0_803:
	s_andn2_b64 vcc, exec, s[2:3]
	s_cbranch_vccnz .LBB0_805
	v_lshl_add_u64 v[12:13], s[12:13], 0, v[160:161]
	global_load_dwordx4 v[8:11], v[12:13], off offset:16 nt
	s_nop 0
	global_load_dwordx4 v[12:15], v[12:13], off nt
.LBB0_805:
	v_readlane_b32 s14, v254, 31
	v_readlane_b32 s15, v254, 32
	s_mov_b64 s[2:3], -1
	s_and_b64 vcc, exec, s[14:15]
	s_cbranch_vccz .LBB0_807
	v_lshl_add_u64 v[16:17], s[0:1], 0, v[68:69]
	global_load_dwordx4 v[16:19], v[16:17], off nt
	s_mov_b64 s[2:3], 0
.LBB0_807:
	s_andn2_b64 vcc, exec, s[2:3]
	s_cbranch_vccnz .LBB0_809
	v_lshl_add_u64 v[20:21], s[0:1], 0, v[66:67]
	global_load_dwordx4 v[16:19], v[20:21], off offset:16 nt
	s_nop 0
	global_load_dwordx4 v[20:23], v[20:21], off nt
.LBB0_809:
	v_readlane_b32 s14, v254, 31
	v_readlane_b32 s15, v254, 32
	s_mov_b64 s[2:3], -1
	s_and_b64 vcc, exec, s[14:15]
	s_cbranch_vccz .LBB0_811
	v_lshl_add_u64 v[24:25], s[12:13], 0, v[68:69]
	global_load_dwordx4 v[24:27], v[24:25], off nt
	s_mov_b64 s[2:3], 0
.LBB0_811:
	s_andn2_b64 vcc, exec, s[2:3]
	s_cbranch_vccnz .LBB0_813
	v_lshl_add_u64 v[28:29], s[12:13], 0, v[66:67]
	global_load_dwordx4 v[24:27], v[28:29], off offset:16 nt
	s_nop 0
	global_load_dwordx4 v[28:31], v[28:29], off nt
.LBB0_813:
	v_readlane_b32 s14, v254, 31
	v_readlane_b32 s15, v254, 32
	s_mov_b64 s[2:3], -1
	s_and_b64 vcc, exec, s[14:15]
	s_cbranch_vccz .LBB0_815
	v_lshl_add_u64 v[32:33], s[0:1], 0, v[72:73]
	global_load_dwordx4 v[32:35], v[32:33], off nt
	s_mov_b64 s[2:3], 0
.LBB0_815:
	s_andn2_b64 vcc, exec, s[2:3]
	s_cbranch_vccnz .LBB0_817
	v_lshl_add_u64 v[36:37], s[0:1], 0, v[70:71]
	global_load_dwordx4 v[32:35], v[36:37], off offset:16 nt
	s_nop 0
	global_load_dwordx4 v[36:39], v[36:37], off nt
.LBB0_817:
	v_readlane_b32 s14, v254, 31
	v_readlane_b32 s15, v254, 32
	s_mov_b64 s[2:3], -1
	s_and_b64 vcc, exec, s[14:15]
	s_cbranch_vccz .LBB0_819
	v_lshl_add_u64 v[40:41], s[12:13], 0, v[72:73]
	global_load_dwordx4 v[40:43], v[40:41], off nt
	s_mov_b64 s[2:3], 0
.LBB0_819:
	s_andn2_b64 vcc, exec, s[2:3]
	s_cbranch_vccnz .LBB0_821
	v_lshl_add_u64 v[44:45], s[12:13], 0, v[70:71]
	global_load_dwordx4 v[40:43], v[44:45], off offset:16 nt
	s_nop 0
	global_load_dwordx4 v[44:47], v[44:45], off nt
.LBB0_821:
	v_readlane_b32 s14, v254, 31
	v_readlane_b32 s15, v254, 32
	s_mov_b64 s[2:3], -1
	s_and_b64 vcc, exec, s[14:15]
	s_cbranch_vccz .LBB0_823
	v_lshl_add_u64 v[48:49], s[0:1], 0, v[76:77]
	global_load_dwordx4 v[52:55], v[48:49], off nt
	s_mov_b64 s[2:3], 0
.LBB0_823:
	s_andn2_b64 vcc, exec, s[2:3]
	s_cbranch_vccnz .LBB0_825
	v_lshl_add_u64 v[48:49], s[0:1], 0, v[74:75]
	global_load_dwordx4 v[52:55], v[48:49], off offset:16 nt
	s_nop 0
	global_load_dwordx4 v[48:51], v[48:49], off nt
.LBB0_825:
	v_readlane_b32 s2, v254, 31
	v_readlane_b32 s3, v254, 32
	s_mov_b64 s[0:1], -1
	s_and_b64 vcc, exec, s[2:3]
	s_cbranch_vccz .LBB0_827
	v_lshl_add_u64 v[56:57], s[12:13], 0, v[76:77]
	global_load_dwordx4 v[60:63], v[56:57], off nt
	s_mov_b64 s[0:1], 0
.LBB0_827:
	s_andn2_b64 vcc, exec, s[0:1]
	s_cbranch_vccnz .LBB0_796
	v_lshl_add_u64 v[56:57], s[12:13], 0, v[74:75]
	global_load_dwordx4 v[60:63], v[56:57], off offset:16 nt
	s_nop 0
	global_load_dwordx4 v[56:59], v[56:57], off nt
	s_branch .LBB0_796
